# scan chunk top LDS read (token-shift mix coefficients) issued before the preceding block barrier; on top of earlier prefetch + last-barrier elimination
# baseline (speedup 1.0000x reference)
.LBB0_483:
	s_or_b64 exec, exec, s[0:1]
	v_readlane_b32 s36, v248, 32
	v_readlane_b32 s37, v248, 33
	v_readlane_b32 s38, v248, 34
	v_readlane_b32 s39, v248, 35
	v_lshl_add_u64 v[92:93], s[36:37], 0, v[40:41]
	s_mov_b32 s28, 0
	v_lshl_add_u64 v[90:91], s[38:39], 0, v[40:41]
	v_mov_b64_e32 v[102:103], v[100:101]
	v_mov_b64_e32 v[104:105], v[100:101]
	v_mov_b64_e32 v[106:107], v[100:101]
	v_mov_b64_e32 v[108:109], v[100:101]
	v_mov_b64_e32 v[110:111], v[100:101]
	v_mov_b64_e32 v[112:113], v[100:101]
	v_mov_b64_e32 v[114:115], v[100:101]
	v_readlane_b32 s40, v248, 36
	v_readlane_b32 s41, v248, 37
	v_readlane_b32 s42, v248, 38
	v_readlane_b32 s43, v248, 39
	s_waitcnt vmcnt(0)
	ds_read_b128 v[8:11], v84 offset:30784
	s_branch .LBB0_485
.LBB0_484:
	s_waitcnt lgkmcnt(0)
	s_barrier
	ds_read_b64 v[20:21], v194 offset:28736
	ds_read_b32 v22, v163 offset:28672
	ds_read_b128 v[8:11], v171 offset:24576
	ds_read_b128 v[12:15], v171 offset:20480
	s_waitcnt lgkmcnt(3)
	v_lshlrev_b32_e32 v116, 16, v20
	v_and_b32_e32 v117, 0xffff0000, v20
	s_waitcnt lgkmcnt(1)
	v_add_f32_e32 v16, v8, v9
	v_add_f32_e32 v16, v16, v10
	v_add_f32_e32 v16, v16, v11
	v_lshlrev_b32_e32 v20, 16, v21
	v_and_b32_e32 v21, 0xffff0000, v21
	v_add_f32_dpp v16, v16, v16 row_ror:8 row_mask:0xf bank_mask:0xf bound_ctrl:1
	s_nop 1
	v_add_f32_dpp v16, v16, v16 row_ror:4 row_mask:0xf bank_mask:0xf bound_ctrl:1
	s_nop 1
	v_add_f32_dpp v16, v16, v16 row_ror:2 row_mask:0xf bank_mask:0xf bound_ctrl:1
	s_nop 1
	v_add_f32_dpp v16, v16, v16 row_ror:1 row_mask:0xf bank_mask:0xf bound_ctrl:1
	v_mul_f32_e32 v16, 0x3c800000, v16
	v_pk_add_f32 v[118:119], v[8:9], v[16:17] op_sel_hi:[1,0] neg_lo:[0,1] neg_hi:[0,1]
	v_pk_add_f32 v[210:211], v[10:11], v[16:17] op_sel_hi:[1,0] neg_lo:[0,1] neg_hi:[0,1]
	v_pk_mul_f32 v[8:9], v[118:119], v[118:119]
	v_pk_mul_f32 v[10:11], v[210:211], v[210:211]
	v_add_f32_e32 v8, v8, v9
	v_add_f32_e32 v8, v10, v8
	v_add_f32_e32 v8, v11, v8
	s_nop 1
	v_add_f32_dpp v8, v8, v8 row_ror:8 row_mask:0xf bank_mask:0xf bound_ctrl:1
	s_nop 1
	v_add_f32_dpp v8, v8, v8 row_ror:4 row_mask:0xf bank_mask:0xf bound_ctrl:1
	s_nop 1
	v_add_f32_dpp v8, v8, v8 row_ror:2 row_mask:0xf bank_mask:0xf bound_ctrl:1
	s_nop 1
	v_add_f32_dpp v8, v8, v8 row_ror:1 row_mask:0xf bank_mask:0xf bound_ctrl:1
	v_fmamk_f32 v8, v8, 0x3c800000, v202
	v_mul_f32_e32 v9, 0x4b800000, v8
	v_cmp_gt_f32_e32 vcc, s68, v8
	s_nop 1
	v_cndmask_b32_e32 v8, v8, v9, vcc
	v_rsq_f32_e32 v23, v8
	ds_read_b128 v[8:11], v205 offset:32320
	ds_read_b128 v[16:19], v205 offset:32576
	v_mul_f32_e32 v40, 0x45800000, v23
	v_cndmask_b32_e32 v40, v23, v40, vcc
	v_pk_mul_f32 v[118:119], v[118:119], v[40:41] op_sel_hi:[1,0]
	s_and_b64 vcc, exec, s[0:1]
	s_waitcnt lgkmcnt(0)
	v_pk_fma_f32 v[8:9], v[8:9], v[118:119], v[16:17]
	s_nop 0
	v_pk_fma_f32 v[8:9], v[12:13], v[22:23], v[8:9] op_sel_hi:[1,0,1]
	v_pk_mul_f32 v[12:13], v[210:211], v[40:41] op_sel_hi:[1,0]
	v_pk_mul_f32 v[8:9], v[8:9], v[116:117]
	v_pk_fma_f32 v[10:11], v[10:11], v[12:13], v[18:19]
	v_cvt_pk_bf16_f32 v8, v8, v9
	v_pk_fma_f32 v[10:11], v[14:15], v[22:23], v[10:11] op_sel_hi:[1,0,1]
	s_nop 0
	v_pk_mul_f32 v[10:11], v[10:11], v[20:21]
	s_nop 0
	v_cvt_pk_bf16_f32 v9, v10, v11
	v_lshl_add_u64 v[10:11], v[70:71], 0, s[28:29]
	v_lshlrev_b64 v[10:11], 11, v[10:11]
	v_lshl_add_u64 v[10:11], v[92:93], 0, v[10:11]
	s_mov_b32 s28, s62
	global_store_dwordx2 v[10:11], v[8:9], off
	ds_read_b128 v[8:11], v84 offset:30784
	s_barrier
	s_cbranch_vccnz .LBB0_472
.LBB0_485:
	s_waitcnt vmcnt(4)
	v_lshlrev_b32_e32 v16, 16, v88
	v_and_b32_e32 v17, 0xffff0000, v88
	s_waitcnt vmcnt(2)
	v_lshlrev_b32_e32 v12, 16, v94
	v_and_b32_e32 v13, 0xffff0000, v94
	v_pk_add_f32 v[18:19], v[12:13], v[16:17] neg_lo:[0,1] neg_hi:[0,1]
	ds_read_b128 v[12:15], v84 offset:31296
	s_waitcnt lgkmcnt(1)
	v_pk_fma_f32 v[8:9], v[18:19], v[8:9], v[16:17]
	v_lshlrev_b32_e32 v16, 16, v89
	v_and_b32_e32 v17, 0xffff0000, v89
	v_lshlrev_b32_e32 v18, 16, v95
	v_and_b32_e32 v19, 0xffff0000, v95
	v_pk_add_f32 v[18:19], v[18:19], v[16:17] neg_lo:[0,1] neg_hi:[0,1]
	v_lshlrev_b32_e32 v222, 16, v76
	v_pk_fma_f32 v[10:11], v[18:19], v[10:11], v[16:17]
	v_lshlrev_b32_e32 v16, 16, v86
	v_and_b32_e32 v17, 0xffff0000, v86
	s_waitcnt vmcnt(1)
	v_lshlrev_b32_e32 v18, 16, v98
	v_and_b32_e32 v19, 0xffff0000, v98
	v_pk_add_f32 v[18:19], v[18:19], v[16:17] neg_lo:[0,1] neg_hi:[0,1]
	ds_write_b128 v171, v[8:11] offset:16384
	s_waitcnt lgkmcnt(1)
	v_pk_fma_f32 v[12:13], v[18:19], v[12:13], v[16:17]
	v_lshlrev_b32_e32 v16, 16, v87
	v_and_b32_e32 v17, 0xffff0000, v87
	v_lshlrev_b32_e32 v18, 16, v99
	v_and_b32_e32 v19, 0xffff0000, v99
	v_pk_add_f32 v[18:19], v[18:19], v[16:17] neg_lo:[0,1] neg_hi:[0,1]
	v_and_b32_e32 v223, 0xffff0000, v76
	v_pk_fma_f32 v[14:15], v[18:19], v[14:15], v[16:17]
	ds_write_b128 v171, v[12:15] offset:20480
	ds_write_b128 v164, v[4:7]
	ds_read_b128 v[12:15], v84 offset:31040
	ds_write_b128 v164, v[0:3] offset:16
	s_waitcnt lgkmcnt(0)
	s_barrier
	ds_read_b128 v[16:19], v196 offset:38464
	ds_read_b128 v[20:23], v197 offset:61248
	ds_read_b128 v[116:119], v196 offset:38528
	ds_read_b128 v[210:213], v197 offset:61312
	ds_read_b128 v[214:217], v196 offset:38592
	s_waitcnt lgkmcnt(3)
	v_mfma_f32_16x16x32_bf16 v[16:19], v[16:19], v[20:23], 0
	ds_read_b128 v[20:23], v197 offset:61376
	ds_read_b128 v[218:221], v196 offset:38656
	v_lshlrev_b32_e32 v224, 16, v96
	v_and_b32_e32 v225, 0xffff0000, v96
	s_waitcnt lgkmcnt(3)
	v_mfma_f32_16x16x32_bf16 v[16:19], v[116:119], v[210:213], v[16:19]
	ds_read_b128 v[116:119], v195 offset:33856
	ds_read_b128 v[210:213], v197 offset:61440
	s_waitcnt lgkmcnt(3)
	v_mfma_f32_16x16x32_bf16 v[16:19], v[214:217], v[20:23], v[16:19]
	ds_read_b128 v[20:23], v167 offset:42816
	ds_read_b128 v[214:217], v195 offset:33920
	s_waitcnt lgkmcnt(2)
	v_mfma_f32_16x16x32_bf16 v[16:19], v[218:221], v[210:213], v[16:19]
	ds_read_b128 v[210:213], v167 offset:42880
	v_pk_add_f32 v[218:219], v[224:225], v[222:223] neg_lo:[0,1] neg_hi:[0,1]
	s_waitcnt lgkmcnt(2)
	v_mfma_f32_16x16x32_bf16 v[20:23], v[116:119], v[20:23], 0
	v_fma_f32 v12, v218, v12, v222
	v_fma_f32 v13, v219, v13, v223
	ds_read_b128 v[116:119], v195 offset:36160
	ds_read_b128 v[218:221], v167 offset:52032
	s_waitcnt lgkmcnt(2)
	v_mfma_f32_16x16x32_bf16 v[20:23], v[214:217], v[210:213], v[20:23]
	ds_read_b128 v[210:213], v195 offset:36224
	ds_read_b128 v[214:217], v167 offset:52096
	s_waitcnt lgkmcnt(2)
	v_mfma_f32_16x16x32_bf16 v[116:119], v[116:119], v[218:221], 0
	s_nop 3
	v_add_f32_e32 v20, v207, v20
	v_mul_f32_e32 v20, 0xbfb8aa3b, v20
	v_exp_f32_e32 v20, v20
	s_waitcnt lgkmcnt(0)
	v_mfma_f32_16x16x32_bf16 v[116:119], v[210:213], v[214:217], v[116:119]
	v_add_f32_e32 v21, v207, v21
	v_mul_f32_e32 v21, 0xbfb8aa3b, v21
	v_add_f32_e32 v20, 1.0, v20
	v_div_scale_f32 v40, s[0:1], v20, v20, 1.0
	v_rcp_f32_e32 v209, v40
	s_nop 2
	v_add_f32_e32 v116, v208, v116
	v_mul_f32_e32 v116, 0xbfb8aa3b, v116
	v_exp_f32_e32 v116, v116
	v_fma_f32 v210, -v40, v209, 1.0
	v_fmac_f32_e32 v209, v210, v209
	v_div_scale_f32 v210, vcc, 1.0, v20, 1.0
	v_mul_f32_e32 v211, v210, v209
	v_fma_f32 v212, -v40, v211, v210
	v_fmac_f32_e32 v211, v212, v209
	v_fma_f32 v40, -v40, v211, v210
	v_div_fmas_f32 v40, v40, v209, v211
	v_div_fixup_f32 v20, v40, v20, 1.0
	v_add_f32_e32 v40, 1.0, v116
	v_div_scale_f32 v116, s[0:1], v40, v40, 1.0
	v_rcp_f32_e32 v209, v116
	v_exp_f32_e32 v21, v21
	v_add_f32_e32 v117, v208, v117
	v_mul_f32_e32 v117, 0xbfb8aa3b, v117
	v_fma_f32 v210, -v116, v209, 1.0
	v_fmac_f32_e32 v209, v210, v209
	v_div_scale_f32 v210, vcc, 1.0, v40, 1.0
	v_mul_f32_e32 v211, v210, v209
	v_fma_f32 v212, -v116, v211, v210
	v_fmac_f32_e32 v211, v212, v209
	v_add_f32_e32 v21, 1.0, v21
	v_fma_f32 v116, -v116, v211, v210
	v_div_scale_f32 v210, s[0:1], v21, v21, 1.0
	v_rcp_f32_e32 v212, v210
	v_div_fmas_f32 v116, v116, v209, v211
	v_exp_f32_e32 v117, v117
	v_mul_f32_e32 v20, 0xbf1b4598, v20
	v_fma_f32 v209, -v210, v212, 1.0
	v_fmac_f32_e32 v212, v209, v212
	v_div_scale_f32 v209, vcc, 1.0, v21, 1.0
	v_mul_f32_e32 v211, v209, v212
	v_fma_f32 v213, -v210, v211, v209
	v_fmac_f32_e32 v211, v213, v212
	v_fma_f32 v209, -v210, v211, v209
	v_div_fmas_f32 v209, v209, v212, v211
	v_div_fixup_f32 v21, v209, v21, 1.0
	v_add_f32_e32 v117, 1.0, v117
	v_mul_f32_e32 v21, 0xbf1b4598, v21
	v_div_scale_f32 v209, s[0:1], v117, v117, 1.0
	v_mul_f32_e32 v20, 0x3fb8aa3b, v20
	v_mul_f32_e32 v21, 0x3fb8aa3b, v21
	v_rcp_f32_e32 v210, v209
	v_exp_f32_e32 v20, v20
	v_exp_f32_e32 v21, v21
	v_div_fixup_f32 v40, v116, v40, 1.0
	v_bfe_u32 v116, v16, 16, 1
	v_add3_u32 v16, v16, v116, s91
	ds_write_b16_d16_hi v199, v16 offset:28736
	ds_write2st64_b32 v198, v20, v21 offset1:1
	v_fma_f32 v16, -v209, v210, 1.0
	v_fmac_f32_e32 v210, v16, v210
	v_div_scale_f32 v16, vcc, 1.0, v117, 1.0
	v_mul_f32_e32 v20, v16, v210
	v_fma_f32 v21, -v209, v20, v16
	v_fmac_f32_e32 v20, v21, v210
	v_add_f32_e32 v21, v207, v22
	v_mul_f32_e32 v21, 0xbfb8aa3b, v21
	v_exp_f32_e32 v21, v21
	v_fma_f32 v16, -v209, v20, v16
	v_div_fmas_f32 v16, v16, v210, v20
	v_div_fixup_f32 v16, v16, v117, 1.0
	ds_write2st64_b32 v198, v40, v16 offset0:96 offset1:97
	v_add_f32_e32 v16, 1.0, v21
	v_div_scale_f32 v20, s[0:1], v16, v16, 1.0
	v_rcp_f32_e32 v21, v20
	v_bfe_u32 v22, v17, 16, 1
	v_add3_u32 v17, v17, v22, s91
	ds_write_b16_d16_hi v199, v17 offset:28864
	v_fma_f32 v17, -v20, v21, 1.0
	v_fmac_f32_e32 v21, v17, v21
	v_div_scale_f32 v17, vcc, 1.0, v16, 1.0
	v_mul_f32_e32 v22, v17, v21
	v_fma_f32 v40, -v20, v22, v17
	v_fmac_f32_e32 v22, v40, v21
	v_fma_f32 v17, -v20, v22, v17
	v_add_f32_e32 v20, v208, v118
	v_mul_f32_e32 v20, 0xbfb8aa3b, v20
	v_exp_f32_e32 v20, v20
	v_div_fmas_f32 v17, v17, v21, v22
	v_div_fixup_f32 v16, v17, v16, 1.0
	v_add_f32_e32 v23, v207, v23
	v_add_f32_e32 v17, 1.0, v20
	v_div_scale_f32 v20, s[0:1], v17, v17, 1.0
	v_rcp_f32_e32 v21, v20
	v_mul_f32_e32 v23, 0xbfb8aa3b, v23
	v_exp_f32_e32 v23, v23
	v_mul_f32_e32 v16, 0xbf1b4598, v16
	v_fma_f32 v22, -v20, v21, 1.0
	v_fmac_f32_e32 v21, v22, v21
	v_div_scale_f32 v22, vcc, 1.0, v17, 1.0
	v_mul_f32_e32 v40, v22, v21
	v_fma_f32 v116, -v20, v40, v22
	v_fmac_f32_e32 v40, v116, v21
	v_fma_f32 v20, -v20, v40, v22
	v_add_f32_e32 v22, 1.0, v23
	v_div_scale_f32 v23, s[0:1], v22, v22, 1.0
	v_rcp_f32_e32 v116, v23
	v_div_fmas_f32 v20, v20, v21, v40
	v_mul_f32_e32 v16, 0x3fb8aa3b, v16
	v_exp_f32_e32 v16, v16
	v_fma_f32 v21, -v23, v116, 1.0
	v_fmac_f32_e32 v116, v21, v116
	v_div_scale_f32 v21, vcc, 1.0, v22, 1.0
	v_mul_f32_e32 v40, v21, v116
	v_fma_f32 v117, -v23, v40, v21
	v_fmac_f32_e32 v40, v117, v116
	v_fma_f32 v21, -v23, v40, v21
	v_div_fmas_f32 v21, v21, v116, v40
	v_div_fixup_f32 v21, v21, v22, 1.0
	v_add_f32_e32 v22, v208, v119
	v_mul_f32_e32 v22, 0xbfb8aa3b, v22
	v_exp_f32_e32 v22, v22
	v_mul_f32_e32 v21, 0xbf1b4598, v21
	v_mul_f32_e32 v21, 0x3fb8aa3b, v21
	v_exp_f32_e32 v21, v21
	v_add_f32_e32 v22, 1.0, v22
	v_div_scale_f32 v23, s[0:1], v22, v22, 1.0
	v_rcp_f32_e32 v40, v23
	v_div_fixup_f32 v17, v20, v17, 1.0
	v_bfe_u32 v20, v18, 16, 1
	v_add3_u32 v18, v18, v20, s91
	ds_write_b16_d16_hi v199, v18 offset:28992
	ds_write2st64_b32 v198, v16, v21 offset0:2 offset1:3
	v_fma_f32 v16, -v23, v40, 1.0
	v_fmac_f32_e32 v40, v16, v40
	v_div_scale_f32 v16, vcc, 1.0, v22, 1.0
	v_mul_f32_e32 v18, v16, v40
	v_fma_f32 v20, -v23, v18, v16
	v_fmac_f32_e32 v18, v20, v40
	v_fma_f32 v16, -v23, v18, v16
	v_div_fmas_f32 v16, v16, v40, v18
	v_div_fixup_f32 v16, v16, v22, 1.0
	ds_write2st64_b32 v198, v17, v16 offset0:98 offset1:99
	v_bfe_u32 v16, v19, 16, 1
	v_add3_u32 v16, v19, v16, s91
	ds_write_b16_d16_hi v199, v16 offset:29120
	s_waitcnt lgkmcnt(0)
	s_barrier
	ds_read_b128 v[16:19], v205 offset:31552
	v_lshlrev_b32_e32 v218, 16, v77
	v_and_b32_e32 v219, 0xffff0000, v77
	v_lshlrev_b32_e32 v20, 16, v97
	v_and_b32_e32 v21, 0xffff0000, v97
	s_cmpk_gt_u32 s28, 0x7ef
	s_cbranch_scc1 .Lscan_nopf
	s_add_i32 s62, s28, 16
	s_movk_i32 s88, 0x1000
	s_mov_b32 s89, 0xfffff000
	v_mov_b32_e32 v255, 0
	v_add_u32_e32 v254, s62, v136
	v_lshl_add_u64 v[0:1], s[58:59], 0, v[254:255]
	v_mad_u64_u32 v[250:251], s[86:87], v0, s90, v[90:91]
	v_mad_i32_i24 v251, v1, s90, v251
	v_add_co_u32_e64 v2, s[84:85], s88, v250
	v_lshlrev_b64 v[0:1], 9, v[0:1]
	s_nop 0
	v_addc_co_u32_e64 v3, s[84:85], 0, v251, s[84:85]
	v_lshl_add_u64 v[4:5], v[42:43], 0, v[0:1]
	v_add_co_u32_e64 v252, s[84:85], s89, v250
	global_load_dwordx2 v[76:77], v[250:251], off offset:2048
	global_load_dwordx2 v[86:87], v[2:3], off
	s_nop 0
	global_load_dwordx4 v[0:3], v[4:5], off offset:16
	s_nop 0
	global_load_dwordx4 v[4:7], v[4:5], off
	v_addc_co_u32_e64 v253, s[84:85], -1, v251, s[84:85]
	global_load_dwordx2 v[88:89], v[250:251], off
	global_load_dwordx2 v[94:95], v[252:253], off offset:-2048
	global_load_dwordx2 v[96:97], v[250:251], off offset:-4096
	global_load_dwordx2 v[98:99], v[250:251], off offset:-2048
